# XCD-local epilogue desynchronisation: odd workgroups start the up-projection phase ~1 us late
# baseline (speedup 1.0000x reference)
;     __device__ void init(int M, int N, int G_, int c_, int vcu) { so.init(M, N, G_, c_); grp = (G_ == (M / BM) * 8); pm = vcu >> 3; j = vcu & 7; nN = N / BM; }
;     __device__ void init(int M, int N, int G_, int c_, int vcu) { so.init(M, N, G_, c_); grp = (G_ == 256 && M == 8192 && N == 6144); b16 = ((vcu >> 5) >> 2) * 16; p = (vcu >> 5) & 3; m = vcu & 31; }
; __global__ void __launch_bounds__(NWAVES * 64, 2) mega_fwd(Args args) {
;     ...
;     if (IN(4)) {
;         pg8::Gemm g{X1B, WUP, M, DFF, DM}; pg8::PanelOrder S; S.init(M, DFF, G, (int)blockIdx.x, vcu);
;         pg8::EpiSqRelu E{UB, (const unsigned*)(ctl + CW_P3D), (N_LAUNCHES != PER_PHASE && G == 256) ? 256u : 0u};
;         pg8::gemm_phase<pg8::EpiSqRelu, pg8::PanelOrder, true, true>(ldsl + RING_OFF, g, S, E);
.LBB0_791:
	s_bitcmp1_b32 s76, 0
	s_cbranch_scc0 .Lp4_nodelay
	s_sleep 24
